# v11 + P14 FPeg epilogue software prefetch (dummy dword loads warm y/pp lines of all 16 iterations)
# baseline (speedup 1.0000x reference)
.LBB0_2141:
	v_lshl_add_u32 v150, s20, 8, v154
	v_lshl_or_b32 v146, s49, 8, v156
	v_ashrrev_i32_e32 v151, 31, v150
	v_lshlrev_b64 v[148:149], 13, v[150:151]
	v_ashrrev_i32_e32 v147, 31, v146
	v_lshl_add_u64 v[160:161], s[6:7], 0, v[148:149]
	v_lshlrev_b64 v[148:149], 1, v[146:147]
	v_lshl_add_u64 v[160:161], v[160:161], 0, v[148:149]
	v_lshlrev_b64 v[168:169], 14, v[150:151]
	global_load_dwordx4 v[164:167], v[160:161], off
	v_lshlrev_b64 v[146:147], 2, v[146:147]
	v_lshl_add_u64 v[168:169], s[28:29], 0, v[168:169]
	v_lshl_add_u64 v[176:177], v[168:169], 0, v[146:147]
	global_load_dwordx4 v[168:171], v[176:177], off
	global_load_dwordx4 v[172:175], v[176:177], off offset:16
	s_mov_b64 s[52:53], 0x40000
	s_mov_b64 s[54:55], 0x140000
	s_mov_b64 s[56:57], 0x20000
	s_mov_b64 s[58:59], 0xa0000
	global_load_dword v184, v[176:177], off offset:512
	global_load_dword v184, v[160:161], off offset:256
	v_mov_b64_e32 v[186:187], v[176:177]
	v_mov_b64_e32 v[188:189], v[160:161]
	v_lshl_add_u64 v[186:187], v[186:187], 0, s[52:53]
	v_lshl_add_u64 v[188:189], v[188:189], 0, s[56:57]
	global_load_dword v184, v[186:187], off
	global_load_dword v184, v[186:187], off offset:512
	global_load_dword v184, v[188:189], off
	global_load_dword v184, v[188:189], off offset:256
	v_lshl_add_u64 v[186:187], v[186:187], 0, s[52:53]
	v_lshl_add_u64 v[188:189], v[188:189], 0, s[56:57]
	global_load_dword v184, v[186:187], off
	global_load_dword v184, v[186:187], off offset:512
	global_load_dword v184, v[188:189], off
	global_load_dword v184, v[188:189], off offset:256
	v_lshl_add_u64 v[186:187], v[186:187], 0, s[52:53]
	v_lshl_add_u64 v[188:189], v[188:189], 0, s[56:57]
	global_load_dword v184, v[186:187], off
	global_load_dword v184, v[186:187], off offset:512
	global_load_dword v184, v[188:189], off
	global_load_dword v184, v[188:189], off offset:256
	v_lshl_add_u64 v[186:187], v[186:187], 0, s[54:55]
	v_lshl_add_u64 v[188:189], v[188:189], 0, s[58:59]
	global_load_dword v184, v[186:187], off
	global_load_dword v184, v[186:187], off offset:512
	global_load_dword v184, v[188:189], off
	global_load_dword v184, v[188:189], off offset:256
	v_lshl_add_u64 v[186:187], v[186:187], 0, s[52:53]
	v_lshl_add_u64 v[188:189], v[188:189], 0, s[56:57]
	global_load_dword v184, v[186:187], off
	global_load_dword v184, v[186:187], off offset:512
	global_load_dword v184, v[188:189], off
	global_load_dword v184, v[188:189], off offset:256
	v_lshl_add_u64 v[186:187], v[186:187], 0, s[52:53]
	v_lshl_add_u64 v[188:189], v[188:189], 0, s[56:57]
	global_load_dword v184, v[186:187], off
	global_load_dword v184, v[186:187], off offset:512
	global_load_dword v184, v[188:189], off
	global_load_dword v184, v[188:189], off offset:256
	v_lshl_add_u64 v[186:187], v[186:187], 0, s[52:53]
	v_lshl_add_u64 v[188:189], v[188:189], 0, s[56:57]
	global_load_dword v184, v[186:187], off
	global_load_dword v184, v[186:187], off offset:512
	global_load_dword v184, v[188:189], off
	global_load_dword v184, v[188:189], off offset:256
	v_mul_f32_e32 v126, 0xbfb8aa3b, v126
	v_mul_f32_e32 v127, 0xbfb8aa3b, v127
	v_mul_f32_e32 v128, 0xbfb8aa3b, v128
	v_mul_f32_e32 v129, 0xbfb8aa3b, v129
	v_mul_f32_e32 v122, 0xbfb8aa3b, v122
	v_mul_f32_e32 v123, 0xbfb8aa3b, v123
	v_mul_f32_e32 v124, 0xbfb8aa3b, v124
	v_mul_f32_e32 v125, 0xbfb8aa3b, v125
	v_exp_f32_e32 v126, v126
	v_exp_f32_e32 v127, v127
	v_exp_f32_e32 v128, v128
	v_exp_f32_e32 v129, v129
	v_exp_f32_e32 v122, v122
	v_exp_f32_e32 v123, v123
	v_exp_f32_e32 v124, v124
	v_exp_f32_e32 v125, v125
	v_add_f32_e32 v126, 1.0, v126
	v_add_f32_e32 v127, 1.0, v127
	v_add_f32_e32 v128, 1.0, v128
	v_add_f32_e32 v129, 1.0, v129
	v_add_f32_e32 v151, 1.0, v122
	v_add_f32_e32 v162, 1.0, v123
	v_add_f32_e32 v178, 1.0, v124
	v_add_f32_e32 v179, 1.0, v125
	v_rcp_f32_e32 v122, v126
	v_rcp_f32_e32 v123, v127
	v_rcp_f32_e32 v124, v128
	v_rcp_f32_e32 v125, v129
	v_rcp_f32_e32 v126, v151
	v_rcp_f32_e32 v127, v162
	v_rcp_f32_e32 v128, v178
	v_rcp_f32_e32 v129, v179
	v_mul_f32_e32 v118, 0xbfb8aa3b, v118
	v_mul_f32_e32 v119, 0xbfb8aa3b, v119
	v_mul_f32_e32 v120, 0xbfb8aa3b, v120
	v_mul_f32_e32 v121, 0xbfb8aa3b, v121
	v_mul_f32_e32 v114, 0xbfb8aa3b, v114
	v_mul_f32_e32 v115, 0xbfb8aa3b, v115
	v_mul_f32_e32 v116, 0xbfb8aa3b, v116
	v_mul_f32_e32 v117, 0xbfb8aa3b, v117
	v_exp_f32_e32 v118, v118
	v_exp_f32_e32 v119, v119
	v_exp_f32_e32 v120, v120
	v_exp_f32_e32 v121, v121
	v_exp_f32_e32 v151, v114
	v_exp_f32_e32 v162, v115
	v_exp_f32_e32 v116, v116
	v_exp_f32_e32 v117, v117
	v_add_f32_e32 v118, 1.0, v118
	v_add_f32_e32 v119, 1.0, v119
	v_add_f32_e32 v120, 1.0, v120
	v_add_f32_e32 v121, 1.0, v121
	v_add_f32_e32 v151, 1.0, v151
	v_add_f32_e32 v162, 1.0, v162
	v_mul_f32_e32 v110, 0xbfb8aa3b, v110
	v_mul_f32_e32 v111, 0xbfb8aa3b, v111
	v_mul_f32_e32 v112, 0xbfb8aa3b, v112
	v_mul_f32_e32 v113, 0xbfb8aa3b, v113
	v_mul_f32_e32 v106, 0xbfb8aa3b, v106
	v_mul_f32_e32 v107, 0xbfb8aa3b, v107
	v_mul_f32_e32 v108, 0xbfb8aa3b, v108
	v_mul_f32_e32 v109, 0xbfb8aa3b, v109
	v_exp_f32_e32 v110, v110
	v_exp_f32_e32 v111, v111
	v_exp_f32_e32 v112, v112
	v_exp_f32_e32 v113, v113
	v_exp_f32_e32 v106, v106
	v_exp_f32_e32 v107, v107
	v_exp_f32_e32 v108, v108
	v_exp_f32_e32 v109, v109
	v_add_f32_e32 v110, 1.0, v110
	v_add_f32_e32 v111, 1.0, v111
	v_add_f32_e32 v112, 1.0, v112
	v_add_f32_e32 v113, 1.0, v113
	v_mul_f32_e32 v102, 0xbfb8aa3b, v102
	s_waitcnt vmcnt(0)
	v_lshlrev_b32_e32 v178, 16, v164
	v_and_b32_e32 v179, 0xffff0000, v164
	v_lshlrev_b32_e32 v164, 16, v165
	v_and_b32_e32 v165, 0xffff0000, v165
	v_lshlrev_b32_e32 v180, 16, v166
	v_and_b32_e32 v181, 0xffff0000, v166
	v_lshlrev_b32_e32 v166, 16, v167
	v_and_b32_e32 v167, 0xffff0000, v167
	v_pk_fma_f32 v[124:125], v[124:125], v[164:165], v[170:171]
	v_pk_fma_f32 v[122:123], v[122:123], v[178:179], v[168:169]
	v_pk_fma_f32 v[128:129], v[128:129], v[166:167], v[174:175]
	v_pk_fma_f32 v[126:127], v[126:127], v[180:181], v[172:173]
	global_store_dwordx4 v[176:177], v[122:125], off
	global_store_dwordx4 v[176:177], v[126:129], off offset:16
	global_load_dwordx4 v[122:125], v[160:161], off offset:256
	s_nop 0
	global_load_dwordx4 v[126:129], v[176:177], off offset:512
	global_load_dwordx4 v[164:167], v[176:177], off offset:528
	v_or_b32_e32 v160, 16, v150
	v_ashrrev_i32_e32 v161, 31, v160
	v_lshlrev_b64 v[114:115], 13, v[160:161]
	v_lshl_add_u64 v[114:115], s[6:7], 0, v[114:115]
	v_add_f32_e32 v170, 1.0, v116
	v_add_f32_e32 v171, 1.0, v117
	v_lshl_add_u64 v[168:169], v[114:115], 0, v[148:149]
	v_rcp_f32_e32 v114, v118
	v_rcp_f32_e32 v115, v119
	v_rcp_f32_e32 v116, v120
	v_rcp_f32_e32 v117, v121
	v_rcp_f32_e32 v118, v151
	v_rcp_f32_e32 v119, v162
	v_rcp_f32_e32 v120, v170
	v_rcp_f32_e32 v121, v171
	v_add_f32_e32 v151, 1.0, v108
	v_rcp_f32_e32 v108, v112
	v_rcp_f32_e32 v112, v151
	v_mul_f32_e32 v103, 0xbfb8aa3b, v103
	v_mul_f32_e32 v104, 0xbfb8aa3b, v104
	v_mul_f32_e32 v105, 0xbfb8aa3b, v105
	v_mul_f32_e32 v98, 0xbfb8aa3b, v98
	v_mul_f32_e32 v99, 0xbfb8aa3b, v99
	v_mul_f32_e32 v100, 0xbfb8aa3b, v100
	v_mul_f32_e32 v101, 0xbfb8aa3b, v101
	v_exp_f32_e32 v102, v102
	v_exp_f32_e32 v103, v103
	v_exp_f32_e32 v104, v104
	v_exp_f32_e32 v105, v105
	v_exp_f32_e32 v100, v100
	v_exp_f32_e32 v101, v101
	v_add_f32_e32 v102, 1.0, v102
	v_add_f32_e32 v103, 1.0, v103
	v_add_f32_e32 v104, 1.0, v104
	v_add_f32_e32 v105, 1.0, v105
	v_mul_f32_e32 v94, 0xbfb8aa3b, v94
	v_mul_f32_e32 v95, 0xbfb8aa3b, v95
	v_mul_f32_e32 v96, 0xbfb8aa3b, v96
	v_mul_f32_e32 v97, 0xbfb8aa3b, v97
	v_mul_f32_e32 v90, 0xbfb8aa3b, v90
	v_mul_f32_e32 v91, 0xbfb8aa3b, v91
	v_mul_f32_e32 v92, 0xbfb8aa3b, v92
	v_mul_f32_e32 v93, 0xbfb8aa3b, v93
	v_exp_f32_e32 v94, v94
	v_exp_f32_e32 v95, v95
	v_exp_f32_e32 v96, v96
	v_exp_f32_e32 v97, v97
	v_exp_f32_e32 v90, v90
	v_exp_f32_e32 v91, v91
	v_exp_f32_e32 v92, v92
	v_exp_f32_e32 v93, v93
	v_add_f32_e32 v94, 1.0, v94
	v_add_f32_e32 v95, 1.0, v95
	v_add_f32_e32 v96, 1.0, v96
	v_add_f32_e32 v97, 1.0, v97
	v_mul_f32_e32 v86, 0xbfb8aa3b, v86
	v_mul_f32_e32 v87, 0xbfb8aa3b, v87
	v_mul_f32_e32 v88, 0xbfb8aa3b, v88
	v_mul_f32_e32 v89, 0xbfb8aa3b, v89
	v_mul_f32_e32 v82, 0xbfb8aa3b, v82
	v_mul_f32_e32 v83, 0xbfb8aa3b, v83
	v_mul_f32_e32 v84, 0xbfb8aa3b, v84
	v_mul_f32_e32 v85, 0xbfb8aa3b, v85
	v_exp_f32_e32 v86, v86
	v_exp_f32_e32 v87, v87
	v_exp_f32_e32 v88, v88
	v_exp_f32_e32 v89, v89
	v_exp_f32_e32 v84, v84
	v_exp_f32_e32 v85, v85
	v_add_f32_e32 v86, 1.0, v86
	v_add_f32_e32 v87, 1.0, v87
	v_add_f32_e32 v88, 1.0, v88
	v_add_f32_e32 v89, 1.0, v89
	v_mul_f32_e32 v78, 0xbfb8aa3b, v78
	v_mul_f32_e32 v79, 0xbfb8aa3b, v79
	v_mul_f32_e32 v80, 0xbfb8aa3b, v80
	v_mul_f32_e32 v81, 0xbfb8aa3b, v81
	s_waitcnt vmcnt(2)
	v_lshlrev_b32_e32 v170, 16, v122
	v_and_b32_e32 v171, 0xffff0000, v122
	v_lshlrev_b32_e32 v122, 16, v123
	v_and_b32_e32 v123, 0xffff0000, v123
	v_lshlrev_b32_e32 v172, 16, v124
	v_and_b32_e32 v173, 0xffff0000, v124
	v_lshlrev_b32_e32 v124, 16, v125
	v_and_b32_e32 v125, 0xffff0000, v125
	s_waitcnt vmcnt(1)
	v_pk_fma_f32 v[116:117], v[116:117], v[122:123], v[128:129]
	v_pk_fma_f32 v[114:115], v[114:115], v[170:171], v[126:127]
	s_waitcnt vmcnt(0)
	v_pk_fma_f32 v[118:119], v[118:119], v[172:173], v[164:165]
	v_pk_fma_f32 v[120:121], v[120:121], v[124:125], v[166:167]
	global_store_dwordx4 v[176:177], v[114:117], off offset:512
	global_store_dwordx4 v[176:177], v[118:121], off offset:528
	global_load_dwordx4 v[114:117], v[168:169], off
	v_add_f32_e32 v128, 1.0, v106
	v_lshlrev_b64 v[118:119], 14, v[160:161]
	v_lshl_add_u64 v[118:119], s[28:29], 0, v[118:119]
	v_lshl_add_u64 v[126:127], v[118:119], 0, v[146:147]
	global_load_dwordx4 v[118:121], v[126:127], off
	global_load_dwordx4 v[122:125], v[126:127], off offset:16
	v_add_f32_e32 v129, 1.0, v107
	v_add_f32_e32 v160, 1.0, v109
	v_rcp_f32_e32 v106, v110
	v_rcp_f32_e32 v107, v111
	v_rcp_f32_e32 v109, v113
	v_rcp_f32_e32 v110, v128
	v_rcp_f32_e32 v111, v129
	v_rcp_f32_e32 v113, v160
	v_mul_f32_e32 v74, 0xbfb8aa3b, v74
	v_mul_f32_e32 v75, 0xbfb8aa3b, v75
	v_mul_f32_e32 v76, 0xbfb8aa3b, v76
	v_mul_f32_e32 v77, 0xbfb8aa3b, v77
	v_exp_f32_e32 v78, v78
	v_exp_f32_e32 v79, v79
	v_exp_f32_e32 v80, v80
	v_exp_f32_e32 v81, v81
	v_exp_f32_e32 v74, v74
	v_exp_f32_e32 v75, v75
	v_exp_f32_e32 v76, v76
	v_exp_f32_e32 v77, v77
	v_add_f32_e32 v78, 1.0, v78
	v_add_f32_e32 v79, 1.0, v79
	v_add_f32_e32 v80, 1.0, v80
	v_add_f32_e32 v81, 1.0, v81
	v_mul_f32_e32 v70, 0xbfb8aa3b, v70
	v_mul_f32_e32 v71, 0xbfb8aa3b, v71
	v_mul_f32_e32 v72, 0xbfb8aa3b, v72
	v_mul_f32_e32 v73, 0xbfb8aa3b, v73
	v_mul_f32_e32 v66, 0xbfb8aa3b, v66
	v_mul_f32_e32 v67, 0xbfb8aa3b, v67
	v_mul_f32_e32 v68, 0xbfb8aa3b, v68
	v_mul_f32_e32 v69, 0xbfb8aa3b, v69
	v_exp_f32_e32 v70, v70
	v_exp_f32_e32 v71, v71
	v_exp_f32_e32 v72, v72
	v_exp_f32_e32 v73, v73
	v_exp_f32_e32 v68, v68
	v_exp_f32_e32 v69, v69
	v_add_f32_e32 v70, 1.0, v70
	v_add_f32_e32 v71, 1.0, v71
	v_add_f32_e32 v72, 1.0, v72
	v_add_f32_e32 v73, 1.0, v73
	v_mul_f32_e32 v62, 0xbfb8aa3b, v62
	v_mul_f32_e32 v63, 0xbfb8aa3b, v63
	v_mul_f32_e32 v64, 0xbfb8aa3b, v64
	v_mul_f32_e32 v65, 0xbfb8aa3b, v65
	v_mul_f32_e32 v58, 0xbfb8aa3b, v58
	v_mul_f32_e32 v59, 0xbfb8aa3b, v59
	v_mul_f32_e32 v60, 0xbfb8aa3b, v60
	v_mul_f32_e32 v61, 0xbfb8aa3b, v61
	v_exp_f32_e32 v62, v62
	v_exp_f32_e32 v63, v63
	v_exp_f32_e32 v64, v64
	v_exp_f32_e32 v65, v65
	v_exp_f32_e32 v58, v58
	v_exp_f32_e32 v59, v59
	v_exp_f32_e32 v60, v60
	v_exp_f32_e32 v61, v61
	v_add_f32_e32 v62, 1.0, v62
	v_add_f32_e32 v63, 1.0, v63
	v_add_f32_e32 v64, 1.0, v64
	v_add_f32_e32 v65, 1.0, v65
	v_mul_f32_e32 v54, 0xbfb8aa3b, v54
	v_mul_f32_e32 v55, 0xbfb8aa3b, v55
	v_mul_f32_e32 v56, 0xbfb8aa3b, v56
	v_mul_f32_e32 v57, 0xbfb8aa3b, v57
	v_mul_f32_e32 v50, 0xbfb8aa3b, v50
	v_mul_f32_e32 v51, 0xbfb8aa3b, v51
	v_mul_f32_e32 v52, 0xbfb8aa3b, v52
	v_mul_f32_e32 v53, 0xbfb8aa3b, v53
	v_exp_f32_e32 v54, v54
	v_exp_f32_e32 v55, v55
	v_exp_f32_e32 v56, v56
	v_exp_f32_e32 v57, v57
	s_waitcnt vmcnt(2)
	v_lshlrev_b32_e32 v128, 16, v114
	v_and_b32_e32 v129, 0xffff0000, v114
	v_lshlrev_b32_e32 v114, 16, v115
	v_and_b32_e32 v115, 0xffff0000, v115
	v_lshlrev_b32_e32 v160, 16, v116
	v_and_b32_e32 v161, 0xffff0000, v116
	v_lshlrev_b32_e32 v116, 16, v117
	v_and_b32_e32 v117, 0xffff0000, v117
	s_waitcnt vmcnt(1)
	v_pk_fma_f32 v[108:109], v[108:109], v[114:115], v[120:121]
	v_pk_fma_f32 v[106:107], v[106:107], v[128:129], v[118:119]
	s_waitcnt vmcnt(0)
	v_pk_fma_f32 v[112:113], v[112:113], v[116:117], v[124:125]
	v_pk_fma_f32 v[110:111], v[110:111], v[160:161], v[122:123]
	global_store_dwordx4 v[126:127], v[106:109], off
	global_store_dwordx4 v[126:127], v[110:113], off offset:16
	global_load_dwordx4 v[106:109], v[168:169], off offset:256
	s_nop 0
	global_load_dwordx4 v[110:113], v[126:127], off offset:512
	global_load_dwordx4 v[114:117], v[126:127], off offset:528
	v_exp_f32_e32 v120, v98
	v_exp_f32_e32 v121, v99
	v_or_b32_e32 v118, 32, v150
	v_ashrrev_i32_e32 v119, 31, v118
	v_lshlrev_b64 v[98:99], 13, v[118:119]
	v_lshl_add_u64 v[98:99], s[6:7], 0, v[98:99]
	v_add_f32_e32 v122, 1.0, v120
	v_add_f32_e32 v123, 1.0, v121
	v_add_f32_e32 v124, 1.0, v100
	v_add_f32_e32 v125, 1.0, v101
	v_lshl_add_u64 v[120:121], v[98:99], 0, v[148:149]
	v_rcp_f32_e32 v98, v102
	v_rcp_f32_e32 v99, v103
	v_rcp_f32_e32 v100, v104
	v_rcp_f32_e32 v101, v105
	v_rcp_f32_e32 v102, v122
	v_rcp_f32_e32 v103, v123
	v_rcp_f32_e32 v104, v124
	v_rcp_f32_e32 v105, v125
	v_exp_f32_e32 v52, v52
	v_exp_f32_e32 v53, v53
	v_add_f32_e32 v54, 1.0, v54
	v_add_f32_e32 v55, 1.0, v55
	v_add_f32_e32 v56, 1.0, v56
	v_add_f32_e32 v57, 1.0, v57
	v_mul_f32_e32 v46, 0xbfb8aa3b, v46
	v_mul_f32_e32 v47, 0xbfb8aa3b, v47
	v_mul_f32_e32 v48, 0xbfb8aa3b, v48
	v_mul_f32_e32 v49, 0xbfb8aa3b, v49
	v_mul_f32_e32 v42, 0xbfb8aa3b, v42
	v_mul_f32_e32 v43, 0xbfb8aa3b, v43
	v_mul_f32_e32 v44, 0xbfb8aa3b, v44
	v_mul_f32_e32 v45, 0xbfb8aa3b, v45
	v_exp_f32_e32 v46, v46
	v_exp_f32_e32 v47, v47
	v_exp_f32_e32 v48, v48
	v_exp_f32_e32 v49, v49
	v_exp_f32_e32 v42, v42
	v_exp_f32_e32 v43, v43
	v_exp_f32_e32 v44, v44
	v_exp_f32_e32 v45, v45
	v_add_f32_e32 v46, 1.0, v46
	v_add_f32_e32 v47, 1.0, v47
	v_add_f32_e32 v48, 1.0, v48
	v_add_f32_e32 v49, 1.0, v49
	v_mul_f32_e32 v38, 0xbfb8aa3b, v38
	v_mul_f32_e32 v39, 0xbfb8aa3b, v39
	v_mul_f32_e32 v40, 0xbfb8aa3b, v40
	v_mul_f32_e32 v41, 0xbfb8aa3b, v41
	v_mul_f32_e32 v34, 0xbfb8aa3b, v34
	v_mul_f32_e32 v35, 0xbfb8aa3b, v35
	v_mul_f32_e32 v36, 0xbfb8aa3b, v36
	v_mul_f32_e32 v37, 0xbfb8aa3b, v37
	v_exp_f32_e32 v38, v38
	v_exp_f32_e32 v39, v39
	v_exp_f32_e32 v40, v40
	v_exp_f32_e32 v41, v41
	v_exp_f32_e32 v36, v36
	v_exp_f32_e32 v37, v37
	v_add_f32_e32 v38, 1.0, v38
	v_add_f32_e32 v39, 1.0, v39
	v_add_f32_e32 v40, 1.0, v40
	v_add_f32_e32 v41, 1.0, v41
	v_mul_f32_e32 v30, 0xbfb8aa3b, v30
	v_mul_f32_e32 v31, 0xbfb8aa3b, v31
	v_mul_f32_e32 v32, 0xbfb8aa3b, v32
	v_mul_f32_e32 v33, 0xbfb8aa3b, v33
	v_mul_f32_e32 v26, 0xbfb8aa3b, v26
	v_mul_f32_e32 v27, 0xbfb8aa3b, v27
	v_mul_f32_e32 v28, 0xbfb8aa3b, v28
	v_mul_f32_e32 v29, 0xbfb8aa3b, v29
	v_exp_f32_e32 v30, v30
	v_exp_f32_e32 v31, v31
	v_exp_f32_e32 v32, v32
	v_exp_f32_e32 v33, v33
	v_exp_f32_e32 v26, v26
	v_exp_f32_e32 v27, v27
	s_waitcnt vmcnt(2)
	v_lshlrev_b32_e32 v122, 16, v106
	v_and_b32_e32 v123, 0xffff0000, v106
	v_lshlrev_b32_e32 v106, 16, v107
	v_and_b32_e32 v107, 0xffff0000, v107
	v_lshlrev_b32_e32 v124, 16, v108
	v_and_b32_e32 v125, 0xffff0000, v108
	v_lshlrev_b32_e32 v108, 16, v109
	v_and_b32_e32 v109, 0xffff0000, v109
	s_waitcnt vmcnt(1)
	v_pk_fma_f32 v[100:101], v[100:101], v[106:107], v[112:113]
	v_pk_fma_f32 v[98:99], v[98:99], v[122:123], v[110:111]
	s_waitcnt vmcnt(0)
	v_pk_fma_f32 v[102:103], v[102:103], v[124:125], v[114:115]
	v_pk_fma_f32 v[104:105], v[104:105], v[108:109], v[116:117]
	global_store_dwordx4 v[126:127], v[98:101], off offset:512
	global_store_dwordx4 v[126:127], v[102:105], off offset:528
	global_load_dwordx4 v[98:101], v[120:121], off
	v_add_f32_e32 v112, 1.0, v90
	v_lshlrev_b64 v[102:103], 14, v[118:119]
	v_lshl_add_u64 v[102:103], s[28:29], 0, v[102:103]
	v_lshl_add_u64 v[110:111], v[102:103], 0, v[146:147]
	global_load_dwordx4 v[102:105], v[110:111], off
	global_load_dwordx4 v[106:109], v[110:111], off offset:16
	v_add_f32_e32 v113, 1.0, v91
	v_add_f32_e32 v114, 1.0, v92
	v_add_f32_e32 v115, 1.0, v93
	v_rcp_f32_e32 v90, v94
	v_rcp_f32_e32 v91, v95
	v_rcp_f32_e32 v92, v96
	v_rcp_f32_e32 v93, v97
	v_rcp_f32_e32 v94, v112
	v_rcp_f32_e32 v95, v113
	v_rcp_f32_e32 v96, v114
	v_rcp_f32_e32 v97, v115
	v_exp_f32_e32 v28, v28
	v_exp_f32_e32 v29, v29
	v_add_f32_e32 v30, 1.0, v30
	v_add_f32_e32 v31, 1.0, v31
	v_add_f32_e32 v32, 1.0, v32
	v_add_f32_e32 v33, 1.0, v33
	v_mul_f32_e32 v22, 0xbfb8aa3b, v22
	v_mul_f32_e32 v23, 0xbfb8aa3b, v23
	v_mul_f32_e32 v24, 0xbfb8aa3b, v24
	v_mul_f32_e32 v25, 0xbfb8aa3b, v25
	v_mul_f32_e32 v18, 0xbfb8aa3b, v18
	v_mul_f32_e32 v19, 0xbfb8aa3b, v19
	v_mul_f32_e32 v20, 0xbfb8aa3b, v20
	v_mul_f32_e32 v21, 0xbfb8aa3b, v21
	v_exp_f32_e32 v22, v22
	v_exp_f32_e32 v23, v23
	v_exp_f32_e32 v24, v24
	v_exp_f32_e32 v25, v25
	v_exp_f32_e32 v20, v20
	v_exp_f32_e32 v21, v21
	v_add_f32_e32 v22, 1.0, v22
	v_add_f32_e32 v23, 1.0, v23
	v_add_f32_e32 v24, 1.0, v24
	v_add_f32_e32 v25, 1.0, v25
	v_mul_f32_e32 v14, 0xbfb8aa3b, v14
	v_mul_f32_e32 v15, 0xbfb8aa3b, v15
	v_mul_f32_e32 v16, 0xbfb8aa3b, v16
	v_mul_f32_e32 v17, 0xbfb8aa3b, v17
	v_mul_f32_e32 v10, 0xbfb8aa3b, v10
	v_mul_f32_e32 v11, 0xbfb8aa3b, v11
	v_mul_f32_e32 v12, 0xbfb8aa3b, v12
	v_mul_f32_e32 v13, 0xbfb8aa3b, v13
	v_exp_f32_e32 v14, v14
	v_exp_f32_e32 v15, v15
	v_exp_f32_e32 v16, v16
	v_exp_f32_e32 v17, v17
	v_exp_f32_e32 v10, v10
	v_exp_f32_e32 v11, v11
	v_exp_f32_e32 v12, v12
	v_exp_f32_e32 v13, v13
	v_add_f32_e32 v14, 1.0, v14
	v_add_f32_e32 v15, 1.0, v15
	v_add_f32_e32 v16, 1.0, v16
	v_add_f32_e32 v17, 1.0, v17
	v_mul_f32_e32 v6, 0xbfb8aa3b, v6
	v_mul_f32_e32 v7, 0xbfb8aa3b, v7
	v_mul_f32_e32 v8, 0xbfb8aa3b, v8
	v_mul_f32_e32 v9, 0xbfb8aa3b, v9
	v_mul_f32_e32 v2, 0xbfb8aa3b, v2
	v_mul_f32_e32 v3, 0xbfb8aa3b, v3
	v_mul_f32_e32 v4, 0xbfb8aa3b, v4
	v_mul_f32_e32 v5, 0xbfb8aa3b, v5
	v_exp_f32_e32 v6, v6
	v_exp_f32_e32 v7, v7
	v_exp_f32_e32 v8, v8
	v_exp_f32_e32 v9, v9
	v_exp_f32_e32 v2, v2
	v_exp_f32_e32 v3, v3
	v_exp_f32_e32 v4, v4
	v_exp_f32_e32 v5, v5
	v_add_f32_e32 v6, 1.0, v6
	v_add_f32_e32 v7, 1.0, v7
	v_add_f32_e32 v8, 1.0, v8
	s_waitcnt vmcnt(2)
	v_lshlrev_b32_e32 v112, 16, v98
	v_and_b32_e32 v113, 0xffff0000, v98
	v_lshlrev_b32_e32 v98, 16, v99
	v_and_b32_e32 v99, 0xffff0000, v99
	v_lshlrev_b32_e32 v114, 16, v100
	v_and_b32_e32 v115, 0xffff0000, v100
	v_lshlrev_b32_e32 v100, 16, v101
	v_and_b32_e32 v101, 0xffff0000, v101
	s_waitcnt vmcnt(1)
	v_pk_fma_f32 v[92:93], v[92:93], v[98:99], v[104:105]
	v_pk_fma_f32 v[90:91], v[90:91], v[112:113], v[102:103]
	s_waitcnt vmcnt(0)
	v_pk_fma_f32 v[96:97], v[96:97], v[100:101], v[108:109]
	v_pk_fma_f32 v[94:95], v[94:95], v[114:115], v[106:107]
	global_store_dwordx4 v[110:111], v[90:93], off
	global_store_dwordx4 v[110:111], v[94:97], off offset:16
	global_load_dwordx4 v[90:93], v[120:121], off offset:256
	s_nop 0
	global_load_dwordx4 v[94:97], v[110:111], off offset:512
	global_load_dwordx4 v[98:101], v[110:111], off offset:528
	v_exp_f32_e32 v104, v82
	v_exp_f32_e32 v105, v83
	v_or_b32_e32 v102, 48, v150
	v_ashrrev_i32_e32 v103, 31, v102
	v_lshlrev_b64 v[82:83], 13, v[102:103]
	v_lshl_add_u64 v[82:83], s[6:7], 0, v[82:83]
	v_add_f32_e32 v106, 1.0, v104
	v_add_f32_e32 v107, 1.0, v105
	v_add_f32_e32 v108, 1.0, v84
	v_add_f32_e32 v109, 1.0, v85
	v_lshl_add_u64 v[104:105], v[82:83], 0, v[148:149]
	v_rcp_f32_e32 v82, v86
	v_rcp_f32_e32 v83, v87
	v_rcp_f32_e32 v84, v88
	v_rcp_f32_e32 v85, v89
	v_rcp_f32_e32 v86, v106
	v_rcp_f32_e32 v87, v107
	v_rcp_f32_e32 v88, v108
	v_rcp_f32_e32 v89, v109
	v_add_f32_e32 v9, 1.0, v9
	s_andn2_b64 vcc, exec, s[0:1]
	s_mov_b64 s[0:1], -1
	s_waitcnt vmcnt(2)
	v_lshlrev_b32_e32 v106, 16, v90
	v_and_b32_e32 v107, 0xffff0000, v90
	v_lshlrev_b32_e32 v90, 16, v91
	v_and_b32_e32 v91, 0xffff0000, v91
	v_lshlrev_b32_e32 v108, 16, v92
	v_and_b32_e32 v109, 0xffff0000, v92
	v_lshlrev_b32_e32 v92, 16, v93
	v_and_b32_e32 v93, 0xffff0000, v93
	s_waitcnt vmcnt(1)
	v_pk_fma_f32 v[84:85], v[84:85], v[90:91], v[96:97]
	v_pk_fma_f32 v[82:83], v[82:83], v[106:107], v[94:95]
	s_waitcnt vmcnt(0)
	v_pk_fma_f32 v[86:87], v[86:87], v[108:109], v[98:99]
	v_pk_fma_f32 v[88:89], v[88:89], v[92:93], v[100:101]
	global_store_dwordx4 v[110:111], v[82:85], off offset:512
	global_store_dwordx4 v[110:111], v[86:89], off offset:528
	global_load_dwordx4 v[82:85], v[104:105], off
	v_add_f32_e32 v96, 1.0, v74
	v_lshlrev_b64 v[86:87], 14, v[102:103]
	v_lshl_add_u64 v[86:87], s[28:29], 0, v[86:87]
	v_lshl_add_u64 v[94:95], v[86:87], 0, v[146:147]
	global_load_dwordx4 v[86:89], v[94:95], off
	global_load_dwordx4 v[90:93], v[94:95], off offset:16
	v_add_f32_e32 v97, 1.0, v75
	v_add_f32_e32 v98, 1.0, v76
	v_add_f32_e32 v99, 1.0, v77
	v_rcp_f32_e32 v74, v78
	v_rcp_f32_e32 v75, v79
	v_rcp_f32_e32 v76, v80
	v_rcp_f32_e32 v77, v81
	v_rcp_f32_e32 v78, v96
	v_rcp_f32_e32 v79, v97
	v_rcp_f32_e32 v80, v98
	v_rcp_f32_e32 v81, v99
	s_waitcnt vmcnt(2)
	v_lshlrev_b32_e32 v96, 16, v82
	v_and_b32_e32 v97, 0xffff0000, v82
	v_lshlrev_b32_e32 v82, 16, v83
	v_and_b32_e32 v83, 0xffff0000, v83
	v_lshlrev_b32_e32 v98, 16, v84
	v_and_b32_e32 v99, 0xffff0000, v84
	v_lshlrev_b32_e32 v84, 16, v85
	v_and_b32_e32 v85, 0xffff0000, v85
	s_waitcnt vmcnt(1)
	v_pk_fma_f32 v[76:77], v[76:77], v[82:83], v[88:89]
	v_pk_fma_f32 v[74:75], v[74:75], v[96:97], v[86:87]
	s_waitcnt vmcnt(0)
	v_pk_fma_f32 v[80:81], v[80:81], v[84:85], v[92:93]
	v_pk_fma_f32 v[78:79], v[78:79], v[98:99], v[90:91]
	global_store_dwordx4 v[94:95], v[74:77], off
	global_store_dwordx4 v[94:95], v[78:81], off offset:16
	global_load_dwordx4 v[74:77], v[104:105], off offset:256
	s_nop 0
	global_load_dwordx4 v[78:81], v[94:95], off offset:512
	global_load_dwordx4 v[82:85], v[94:95], off offset:528
	v_exp_f32_e32 v88, v66
	v_exp_f32_e32 v89, v67
	v_add_u32_e32 v86, 0x80, v150
	v_ashrrev_i32_e32 v87, 31, v86
	v_lshlrev_b64 v[66:67], 13, v[86:87]
	v_lshl_add_u64 v[66:67], s[6:7], 0, v[66:67]
	v_add_f32_e32 v90, 1.0, v88
	v_add_f32_e32 v91, 1.0, v89
	v_add_f32_e32 v92, 1.0, v68
	v_add_f32_e32 v93, 1.0, v69
	v_lshl_add_u64 v[88:89], v[66:67], 0, v[148:149]
	v_rcp_f32_e32 v66, v70
	v_rcp_f32_e32 v67, v71
	v_rcp_f32_e32 v68, v72
	v_rcp_f32_e32 v69, v73
	v_rcp_f32_e32 v70, v90
	v_rcp_f32_e32 v71, v91
	v_rcp_f32_e32 v72, v92
	v_rcp_f32_e32 v73, v93
	s_waitcnt vmcnt(2)
	v_lshlrev_b32_e32 v90, 16, v74
	v_and_b32_e32 v91, 0xffff0000, v74
	v_lshlrev_b32_e32 v74, 16, v75
	v_and_b32_e32 v75, 0xffff0000, v75
	v_lshlrev_b32_e32 v92, 16, v76
	v_and_b32_e32 v93, 0xffff0000, v76
	v_lshlrev_b32_e32 v76, 16, v77
	v_and_b32_e32 v77, 0xffff0000, v77
	s_waitcnt vmcnt(1)
	v_pk_fma_f32 v[68:69], v[68:69], v[74:75], v[80:81]
	v_pk_fma_f32 v[66:67], v[66:67], v[90:91], v[78:79]
	s_waitcnt vmcnt(0)
	v_pk_fma_f32 v[70:71], v[70:71], v[92:93], v[82:83]
	v_pk_fma_f32 v[72:73], v[72:73], v[76:77], v[84:85]
	global_store_dwordx4 v[94:95], v[66:69], off offset:512
	global_store_dwordx4 v[94:95], v[70:73], off offset:528
	global_load_dwordx4 v[66:69], v[88:89], off
	v_add_f32_e32 v80, 1.0, v58
	v_lshlrev_b64 v[70:71], 14, v[86:87]
	v_lshl_add_u64 v[70:71], s[28:29], 0, v[70:71]
	v_lshl_add_u64 v[78:79], v[70:71], 0, v[146:147]
	global_load_dwordx4 v[70:73], v[78:79], off
	global_load_dwordx4 v[74:77], v[78:79], off offset:16
	v_add_f32_e32 v81, 1.0, v59
	v_add_f32_e32 v82, 1.0, v60
	v_add_f32_e32 v83, 1.0, v61
	v_rcp_f32_e32 v58, v62
	v_rcp_f32_e32 v59, v63
	v_rcp_f32_e32 v60, v64
	v_rcp_f32_e32 v61, v65
	v_rcp_f32_e32 v62, v80
	v_rcp_f32_e32 v63, v81
	v_rcp_f32_e32 v64, v82
	v_rcp_f32_e32 v65, v83
	s_waitcnt vmcnt(2)
	v_lshlrev_b32_e32 v80, 16, v66
	v_and_b32_e32 v81, 0xffff0000, v66
	v_lshlrev_b32_e32 v66, 16, v67
	v_and_b32_e32 v67, 0xffff0000, v67
	v_lshlrev_b32_e32 v82, 16, v68
	v_and_b32_e32 v83, 0xffff0000, v68
	v_lshlrev_b32_e32 v68, 16, v69
	v_and_b32_e32 v69, 0xffff0000, v69
	s_waitcnt vmcnt(1)
	v_pk_fma_f32 v[60:61], v[60:61], v[66:67], v[72:73]
	v_pk_fma_f32 v[58:59], v[58:59], v[80:81], v[70:71]
	s_waitcnt vmcnt(0)
	v_pk_fma_f32 v[64:65], v[64:65], v[68:69], v[76:77]
	v_pk_fma_f32 v[62:63], v[62:63], v[82:83], v[74:75]
	global_store_dwordx4 v[78:79], v[58:61], off
	global_store_dwordx4 v[78:79], v[62:65], off offset:16
	global_load_dwordx4 v[58:61], v[88:89], off offset:256
	s_nop 0
	global_load_dwordx4 v[62:65], v[78:79], off offset:512
	global_load_dwordx4 v[66:69], v[78:79], off offset:528
	v_exp_f32_e32 v72, v50
	v_exp_f32_e32 v73, v51
	v_add_u32_e32 v70, 0x90, v150
	v_ashrrev_i32_e32 v71, 31, v70
	v_lshlrev_b64 v[50:51], 13, v[70:71]
	v_lshl_add_u64 v[50:51], s[6:7], 0, v[50:51]
	v_add_f32_e32 v74, 1.0, v72
	v_add_f32_e32 v75, 1.0, v73
	v_add_f32_e32 v76, 1.0, v52
	v_add_f32_e32 v77, 1.0, v53
	v_lshl_add_u64 v[72:73], v[50:51], 0, v[148:149]
	v_rcp_f32_e32 v50, v54
	v_rcp_f32_e32 v51, v55
	v_rcp_f32_e32 v52, v56
	v_rcp_f32_e32 v53, v57
	v_rcp_f32_e32 v54, v74
	v_rcp_f32_e32 v55, v75
	v_rcp_f32_e32 v56, v76
	v_rcp_f32_e32 v57, v77
	s_waitcnt vmcnt(2)
	v_lshlrev_b32_e32 v74, 16, v58
	v_and_b32_e32 v75, 0xffff0000, v58
	v_lshlrev_b32_e32 v58, 16, v59
	v_and_b32_e32 v59, 0xffff0000, v59
	v_lshlrev_b32_e32 v76, 16, v60
	v_and_b32_e32 v77, 0xffff0000, v60
	v_lshlrev_b32_e32 v60, 16, v61
	v_and_b32_e32 v61, 0xffff0000, v61
	s_waitcnt vmcnt(1)
	v_pk_fma_f32 v[52:53], v[52:53], v[58:59], v[64:65]
	v_pk_fma_f32 v[50:51], v[50:51], v[74:75], v[62:63]
	s_waitcnt vmcnt(0)
	v_pk_fma_f32 v[54:55], v[54:55], v[76:77], v[66:67]
	v_pk_fma_f32 v[56:57], v[56:57], v[60:61], v[68:69]
	global_store_dwordx4 v[78:79], v[50:53], off offset:512
	global_store_dwordx4 v[78:79], v[54:57], off offset:528
	global_load_dwordx4 v[50:53], v[72:73], off
	v_add_f32_e32 v64, 1.0, v42
	v_lshlrev_b64 v[54:55], 14, v[70:71]
	v_lshl_add_u64 v[54:55], s[28:29], 0, v[54:55]
	v_lshl_add_u64 v[62:63], v[54:55], 0, v[146:147]
	global_load_dwordx4 v[54:57], v[62:63], off
	global_load_dwordx4 v[58:61], v[62:63], off offset:16
	v_add_f32_e32 v65, 1.0, v43
	v_add_f32_e32 v66, 1.0, v44
	v_add_f32_e32 v67, 1.0, v45
	v_rcp_f32_e32 v42, v46
	v_rcp_f32_e32 v43, v47
	v_rcp_f32_e32 v44, v48
	v_rcp_f32_e32 v45, v49
	v_rcp_f32_e32 v46, v64
	v_rcp_f32_e32 v47, v65
	v_rcp_f32_e32 v48, v66
	v_rcp_f32_e32 v49, v67
	s_waitcnt vmcnt(2)
	v_lshlrev_b32_e32 v64, 16, v50
	v_and_b32_e32 v65, 0xffff0000, v50
	v_lshlrev_b32_e32 v50, 16, v51
	v_and_b32_e32 v51, 0xffff0000, v51
	v_lshlrev_b32_e32 v66, 16, v52
	v_and_b32_e32 v67, 0xffff0000, v52
	v_lshlrev_b32_e32 v52, 16, v53
	v_and_b32_e32 v53, 0xffff0000, v53
	s_waitcnt vmcnt(1)
	v_pk_fma_f32 v[44:45], v[44:45], v[50:51], v[56:57]
	v_pk_fma_f32 v[42:43], v[42:43], v[64:65], v[54:55]
	s_waitcnt vmcnt(0)
	v_pk_fma_f32 v[48:49], v[48:49], v[52:53], v[60:61]
	v_pk_fma_f32 v[46:47], v[46:47], v[66:67], v[58:59]
	global_store_dwordx4 v[62:63], v[42:45], off
	global_store_dwordx4 v[62:63], v[46:49], off offset:16
	global_load_dwordx4 v[42:45], v[72:73], off offset:256
	s_nop 0
	global_load_dwordx4 v[46:49], v[62:63], off offset:512
	global_load_dwordx4 v[50:53], v[62:63], off offset:528
	v_exp_f32_e32 v56, v34
	v_exp_f32_e32 v57, v35
	v_add_u32_e32 v54, 0xa0, v150
	v_ashrrev_i32_e32 v55, 31, v54
	v_lshlrev_b64 v[34:35], 13, v[54:55]
	v_lshl_add_u64 v[34:35], s[6:7], 0, v[34:35]
	v_add_f32_e32 v58, 1.0, v56
	v_add_f32_e32 v59, 1.0, v57
	v_add_f32_e32 v60, 1.0, v36
	v_add_f32_e32 v61, 1.0, v37
	v_lshl_add_u64 v[56:57], v[34:35], 0, v[148:149]
	v_rcp_f32_e32 v34, v38
	v_rcp_f32_e32 v35, v39
	v_rcp_f32_e32 v36, v40
	v_rcp_f32_e32 v37, v41
	v_rcp_f32_e32 v38, v58
	v_rcp_f32_e32 v39, v59
	v_rcp_f32_e32 v40, v60
	v_rcp_f32_e32 v41, v61
	s_waitcnt vmcnt(2)
	v_lshlrev_b32_e32 v58, 16, v42
	v_and_b32_e32 v59, 0xffff0000, v42
	v_lshlrev_b32_e32 v42, 16, v43
	v_and_b32_e32 v43, 0xffff0000, v43
	v_lshlrev_b32_e32 v60, 16, v44
	v_and_b32_e32 v61, 0xffff0000, v44
	v_lshlrev_b32_e32 v44, 16, v45
	v_and_b32_e32 v45, 0xffff0000, v45
	s_waitcnt vmcnt(1)
	v_pk_fma_f32 v[36:37], v[36:37], v[42:43], v[48:49]
	v_pk_fma_f32 v[34:35], v[34:35], v[58:59], v[46:47]
	s_waitcnt vmcnt(0)
	v_pk_fma_f32 v[38:39], v[38:39], v[60:61], v[50:51]
	v_pk_fma_f32 v[40:41], v[40:41], v[44:45], v[52:53]
	global_store_dwordx4 v[62:63], v[34:37], off offset:512
	global_store_dwordx4 v[62:63], v[38:41], off offset:528
	global_load_dwordx4 v[34:37], v[56:57], off
	v_add_f32_e32 v48, 1.0, v26
	v_lshlrev_b64 v[38:39], 14, v[54:55]
	v_lshl_add_u64 v[38:39], s[28:29], 0, v[38:39]
	v_lshl_add_u64 v[46:47], v[38:39], 0, v[146:147]
	global_load_dwordx4 v[38:41], v[46:47], off
	global_load_dwordx4 v[42:45], v[46:47], off offset:16
	v_add_f32_e32 v49, 1.0, v27
	v_add_f32_e32 v50, 1.0, v28
	v_add_f32_e32 v51, 1.0, v29
	v_rcp_f32_e32 v26, v30
	v_rcp_f32_e32 v27, v31
	v_rcp_f32_e32 v28, v32
	v_rcp_f32_e32 v29, v33
	v_rcp_f32_e32 v30, v48
	v_rcp_f32_e32 v31, v49
	v_rcp_f32_e32 v32, v50
	v_rcp_f32_e32 v33, v51
	s_waitcnt vmcnt(2)
	v_lshlrev_b32_e32 v48, 16, v34
	v_and_b32_e32 v49, 0xffff0000, v34
	v_lshlrev_b32_e32 v34, 16, v35
	v_and_b32_e32 v35, 0xffff0000, v35
	v_lshlrev_b32_e32 v50, 16, v36
	v_and_b32_e32 v51, 0xffff0000, v36
	v_lshlrev_b32_e32 v36, 16, v37
	v_and_b32_e32 v37, 0xffff0000, v37
	s_waitcnt vmcnt(1)
	v_pk_fma_f32 v[28:29], v[28:29], v[34:35], v[40:41]
	v_pk_fma_f32 v[26:27], v[26:27], v[48:49], v[38:39]
	s_waitcnt vmcnt(0)
	v_pk_fma_f32 v[32:33], v[32:33], v[36:37], v[44:45]
	v_pk_fma_f32 v[30:31], v[30:31], v[50:51], v[42:43]
	global_store_dwordx4 v[46:47], v[26:29], off
	global_store_dwordx4 v[46:47], v[30:33], off offset:16
	global_load_dwordx4 v[26:29], v[56:57], off offset:256
	s_nop 0
	global_load_dwordx4 v[30:33], v[46:47], off offset:512
	global_load_dwordx4 v[34:37], v[46:47], off offset:528
	v_exp_f32_e32 v40, v18
	v_exp_f32_e32 v41, v19
	v_add_u32_e32 v38, 0xb0, v150
	v_ashrrev_i32_e32 v39, 31, v38
	v_lshlrev_b64 v[18:19], 13, v[38:39]
	v_lshl_add_u64 v[18:19], s[6:7], 0, v[18:19]
	v_add_f32_e32 v42, 1.0, v40
	v_add_f32_e32 v43, 1.0, v41
	v_add_f32_e32 v44, 1.0, v20
	v_add_f32_e32 v45, 1.0, v21
	v_lshl_add_u64 v[40:41], v[18:19], 0, v[148:149]
	v_rcp_f32_e32 v18, v22
	v_rcp_f32_e32 v19, v23
	v_rcp_f32_e32 v20, v24
	v_rcp_f32_e32 v21, v25
	v_rcp_f32_e32 v22, v42
	v_rcp_f32_e32 v23, v43
	v_rcp_f32_e32 v24, v44
	v_rcp_f32_e32 v25, v45
	s_waitcnt vmcnt(2)
	v_lshlrev_b32_e32 v42, 16, v26
	v_and_b32_e32 v43, 0xffff0000, v26
	v_lshlrev_b32_e32 v26, 16, v27
	v_and_b32_e32 v27, 0xffff0000, v27
	v_lshlrev_b32_e32 v44, 16, v28
	v_and_b32_e32 v45, 0xffff0000, v28
	v_lshlrev_b32_e32 v28, 16, v29
	v_and_b32_e32 v29, 0xffff0000, v29
	s_waitcnt vmcnt(1)
	v_pk_fma_f32 v[20:21], v[20:21], v[26:27], v[32:33]
	v_pk_fma_f32 v[18:19], v[18:19], v[42:43], v[30:31]
	s_waitcnt vmcnt(0)
	v_pk_fma_f32 v[22:23], v[22:23], v[44:45], v[34:35]
	v_pk_fma_f32 v[24:25], v[24:25], v[28:29], v[36:37]
	global_store_dwordx4 v[46:47], v[18:21], off offset:512
	global_store_dwordx4 v[46:47], v[22:25], off offset:528
	global_load_dwordx4 v[18:21], v[40:41], off
	v_add_f32_e32 v32, 1.0, v10
	v_lshlrev_b64 v[22:23], 14, v[38:39]
	v_lshl_add_u64 v[22:23], s[28:29], 0, v[22:23]
	v_lshl_add_u64 v[30:31], v[22:23], 0, v[146:147]
	global_load_dwordx4 v[22:25], v[30:31], off
	global_load_dwordx4 v[26:29], v[30:31], off offset:16
	v_add_f32_e32 v33, 1.0, v11
	v_add_f32_e32 v34, 1.0, v12
	v_add_f32_e32 v35, 1.0, v13
	v_rcp_f32_e32 v10, v14
	v_rcp_f32_e32 v11, v15
	v_rcp_f32_e32 v12, v16
	v_rcp_f32_e32 v13, v17
	v_rcp_f32_e32 v14, v32
	v_rcp_f32_e32 v15, v33
	v_rcp_f32_e32 v16, v34
	v_rcp_f32_e32 v17, v35
	s_waitcnt vmcnt(2)
	v_lshlrev_b32_e32 v32, 16, v18
	v_and_b32_e32 v33, 0xffff0000, v18
	v_lshlrev_b32_e32 v18, 16, v19
	v_and_b32_e32 v19, 0xffff0000, v19
	v_lshlrev_b32_e32 v34, 16, v20
	v_and_b32_e32 v35, 0xffff0000, v20
	v_lshlrev_b32_e32 v20, 16, v21
	v_and_b32_e32 v21, 0xffff0000, v21
	s_waitcnt vmcnt(1)
	v_pk_fma_f32 v[12:13], v[12:13], v[18:19], v[24:25]
	v_pk_fma_f32 v[10:11], v[10:11], v[32:33], v[22:23]
	s_waitcnt vmcnt(0)
	v_pk_fma_f32 v[16:17], v[16:17], v[20:21], v[28:29]
	v_pk_fma_f32 v[14:15], v[14:15], v[34:35], v[26:27]
	global_store_dwordx4 v[30:31], v[10:13], off
	global_store_dwordx4 v[30:31], v[14:17], off offset:16
	global_load_dwordx4 v[10:13], v[40:41], off offset:256
	s_nop 0
	global_load_dwordx4 v[14:17], v[30:31], off offset:512
	global_load_dwordx4 v[18:21], v[30:31], off offset:528
	v_add_f32_e32 v22, 1.0, v2
	v_add_f32_e32 v23, 1.0, v3
	v_add_f32_e32 v24, 1.0, v4
	v_add_f32_e32 v25, 1.0, v5
	v_rcp_f32_e32 v2, v6
	v_rcp_f32_e32 v3, v7
	v_rcp_f32_e32 v4, v8
	v_rcp_f32_e32 v5, v9
	v_rcp_f32_e32 v6, v22
	v_rcp_f32_e32 v7, v23
	v_rcp_f32_e32 v8, v24
	v_rcp_f32_e32 v9, v25
	s_waitcnt vmcnt(2)
	v_lshlrev_b32_e32 v22, 16, v10
	v_and_b32_e32 v23, 0xffff0000, v10
	v_lshlrev_b32_e32 v10, 16, v11
	v_and_b32_e32 v11, 0xffff0000, v11
	v_lshlrev_b32_e32 v24, 16, v12
	v_and_b32_e32 v25, 0xffff0000, v12
	v_lshlrev_b32_e32 v12, 16, v13
	v_and_b32_e32 v13, 0xffff0000, v13
	s_waitcnt vmcnt(1)
	v_pk_fma_f32 v[4:5], v[4:5], v[10:11], v[16:17]
	v_pk_fma_f32 v[2:3], v[2:3], v[22:23], v[14:15]
	s_waitcnt vmcnt(0)
	v_pk_fma_f32 v[8:9], v[8:9], v[12:13], v[20:21]
	v_pk_fma_f32 v[6:7], v[6:7], v[24:25], v[18:19]
	global_store_dwordx4 v[30:31], v[2:5], off offset:512
	global_store_dwordx4 v[30:31], v[6:9], off offset:528
	s_cbranch_vccnz .LBB0_2134
	s_andn2_b64 vcc, exec, s[4:5]
	s_cbranch_vccnz .LBB0_2133
	s_barrier
	s_branch .LBB0_2133
